# down-proj EpiRes epilogue (layers 0,3): the 8 residual/modulation loads of each row block issued together before one wait instead of 4 serialized load-wait-store round trips
# baseline (speedup 1.0000x reference)
.LBB0_1865:
	s_lshl_b32 s24, s50, 8
	s_add_i32 s24, s24, s40
	v_or_b32_e32 v148, s24, v154
	s_movk_i32 s0, 0x4020
	v_lshl_or_b32 v146, s49, 8, v156
	s_ashr_i32 s25, s24, 13
	v_cmp_gt_i32_e32 vcc, s0, v148
	s_and_saveexec_b64 s[22:23], vcc
	s_cbranch_execz .LBB0_1871
	s_movk_i32 s0, 0x4000
	v_cmp_gt_i32_e32 vcc, s0, v148
	s_movk_i32 s0, 0x3fff
	v_cmp_lt_i32_e64 s[0:1], s0, v148
	s_and_saveexec_b64 s[26:27], s[0:1]
	s_xor_b64 s[0:1], exec, s[26:27]
	v_add_u32_e32 v2, 0xffffc000, v148
	v_lshlrev_b64 v[150:151], 12, v[2:3]
	v_mov_b32_e32 v149, v3
	v_lshl_add_u64 v[152:153], v[132:133], 0, v[150:151]
	v_lshlrev_b64 v[150:151], 12, v[148:149]
	s_andn2_saveexec_b64 s[0:1], s[0:1]
	v_ashrrev_i32_e32 v149, 31, v148
	v_lshlrev_b64 v[150:151], 12, v[148:149]
	v_lshl_add_u64 v[152:153], s[12:13], 0, v[150:151]
	s_or_b64 exec, exec, s[0:1]
	v_add_u32_e32 v2, 0xffffc002, v148
	v_mov_b32_e32 v147, s25
	v_cndmask_b32_e32 v2, v2, v147, vcc
	v_ashrrev_i32_e32 v147, 31, v146
	s_mov_b32 s0, 0x1a000
	v_lshlrev_b64 v[166:167], 2, v[146:147]
	v_mad_i64_i32 v[158:159], s[0:1], v2, s0, v[140:141]
	v_lshl_add_u64 v[170:171], v[152:153], 0, v[166:167]
	v_lshl_add_u64 v[168:169], v[158:159], 0, v[166:167]
	global_load_dwordx4 v[180:183], v[170:171], off
	global_load_dwordx4 v[184:187], v[168:169], off
	global_load_dwordx4 v[188:191], v[168:169], off offset:64
	global_load_dwordx4 v[192:195], v[170:171], off offset:64
	global_load_dwordx4 v[196:199], v[168:169], off offset:512
	global_load_dwordx4 v[202:205], v[170:171], off offset:512
	global_load_dwordx4 v[206:209], v[168:169], off offset:576
	global_load_dwordx4 v[210:213], v[170:171], off offset:576
	v_lshl_add_u64 v[150:151], s[12:13], 0, v[150:151]
	v_lshl_add_u64 v[166:167], v[150:151], 0, v[166:167]
	s_waitcnt vmcnt(0)
	v_pk_fma_f32 v[130:131], v[130:131], v[186:187], v[182:183]
	v_pk_fma_f32 v[128:129], v[128:129], v[184:185], v[180:181]
	global_store_dwordx4 v[166:167], v[128:131], off
	v_pk_fma_f32 v[126:127], v[126:127], v[190:191], v[194:195]
	v_pk_fma_f32 v[124:125], v[124:125], v[188:189], v[192:193]
	global_store_dwordx4 v[166:167], v[124:127], off offset:64
	v_pk_fma_f32 v[122:123], v[122:123], v[198:199], v[204:205]
	v_pk_fma_f32 v[120:121], v[120:121], v[196:197], v[202:203]
	global_store_dwordx4 v[166:167], v[120:123], off offset:512
	v_pk_fma_f32 v[118:119], v[118:119], v[208:209], v[212:213]
	v_pk_fma_f32 v[116:117], v[116:117], v[206:207], v[210:211]
	global_store_dwordx4 v[166:167], v[116:119], off offset:576
.LBB0_1871:
	s_or_b64 exec, exec, s[22:23]
	s_nop 0
	v_or_b32_e32 v116, 16, v148
	s_movk_i32 s0, 0x4020
	v_cmp_gt_i32_e32 vcc, s0, v116
	s_and_saveexec_b64 s[22:23], vcc
	s_mov_b64 s[54:55], 0x9400380
	s_cbranch_execz .LBB0_1877
	s_movk_i32 s0, 0x4000
	v_cmp_gt_i32_e32 vcc, s0, v116
	s_movk_i32 s0, 0x3fff
	v_cmp_lt_i32_e64 s[0:1], s0, v116
	s_and_saveexec_b64 s[26:27], s[0:1]
	s_xor_b64 s[0:1], exec, s[26:27]
	v_add_u32_e32 v2, 0xffffc010, v148
	v_lshlrev_b64 v[118:119], 12, v[2:3]
	v_mov_b32_e32 v117, v3
	v_lshl_add_u64 v[120:121], v[132:133], 0, v[118:119]
	v_lshlrev_b64 v[118:119], 12, v[116:117]
	s_andn2_saveexec_b64 s[0:1], s[0:1]
	v_ashrrev_i32_e32 v117, 31, v116
	v_lshlrev_b64 v[118:119], 12, v[116:117]
	v_lshl_add_u64 v[120:121], s[12:13], 0, v[118:119]
	s_or_b64 exec, exec, s[0:1]
	v_add_u32_e32 v2, 0xffffc012, v148
	v_mov_b32_e32 v116, s25
	v_ashrrev_i32_e32 v147, 31, v146
	v_cndmask_b32_e32 v2, v2, v116, vcc
	s_mov_b32 s0, 0x1a000
	v_lshlrev_b64 v[128:129], 2, v[146:147]
	v_mad_i64_i32 v[116:117], s[0:1], v2, s0, v[140:141]
	v_lshl_add_u64 v[150:151], v[120:121], 0, v[128:129]
	v_lshl_add_u64 v[130:131], v[116:117], 0, v[128:129]
	global_load_dwordx4 v[180:183], v[150:151], off
	global_load_dwordx4 v[184:187], v[130:131], off
	global_load_dwordx4 v[188:191], v[130:131], off offset:64
	global_load_dwordx4 v[192:195], v[150:151], off offset:64
	global_load_dwordx4 v[196:199], v[130:131], off offset:512
	global_load_dwordx4 v[202:205], v[150:151], off offset:512
	global_load_dwordx4 v[206:209], v[130:131], off offset:576
	global_load_dwordx4 v[210:213], v[150:151], off offset:576
	v_lshl_add_u64 v[116:117], s[12:13], 0, v[118:119]
	v_lshl_add_u64 v[128:129], v[116:117], 0, v[128:129]
	s_waitcnt vmcnt(0)
	v_pk_fma_f32 v[114:115], v[114:115], v[186:187], v[182:183]
	v_pk_fma_f32 v[112:113], v[112:113], v[184:185], v[180:181]
	global_store_dwordx4 v[128:129], v[112:115], off
	v_pk_fma_f32 v[110:111], v[110:111], v[190:191], v[194:195]
	v_pk_fma_f32 v[108:109], v[108:109], v[188:189], v[192:193]
	global_store_dwordx4 v[128:129], v[108:111], off offset:64
	v_pk_fma_f32 v[106:107], v[106:107], v[198:199], v[204:205]
	v_pk_fma_f32 v[104:105], v[104:105], v[196:197], v[202:203]
	global_store_dwordx4 v[128:129], v[104:107], off offset:512
	v_pk_fma_f32 v[102:103], v[102:103], v[208:209], v[212:213]
	v_pk_fma_f32 v[100:101], v[100:101], v[206:207], v[210:211]
	global_store_dwordx4 v[128:129], v[100:103], off offset:576
.LBB0_1877:
	s_or_b64 exec, exec, s[22:23]
	v_or_b32_e32 v104, 32, v148
	s_movk_i32 s0, 0x4020
	v_cmp_gt_i32_e32 vcc, s0, v104
	s_and_saveexec_b64 s[22:23], vcc
	s_cbranch_execz .LBB0_1883
	s_movk_i32 s0, 0x4000
	v_cmp_gt_i32_e32 vcc, s0, v104
	s_movk_i32 s0, 0x3fff
	v_cmp_lt_i32_e64 s[0:1], s0, v104
	s_and_saveexec_b64 s[26:27], s[0:1]
	s_xor_b64 s[0:1], exec, s[26:27]
	v_add_u32_e32 v2, 0xffffc020, v148
	v_lshlrev_b64 v[100:101], 12, v[2:3]
	v_mov_b32_e32 v105, v3
	v_lshl_add_u64 v[102:103], v[132:133], 0, v[100:101]
	v_lshlrev_b64 v[100:101], 12, v[104:105]
	s_andn2_saveexec_b64 s[0:1], s[0:1]
	v_ashrrev_i32_e32 v105, 31, v104
	v_lshlrev_b64 v[100:101], 12, v[104:105]
	v_lshl_add_u64 v[102:103], s[12:13], 0, v[100:101]
	s_or_b64 exec, exec, s[0:1]
	v_add_u32_e32 v2, 0xffffc022, v148
	v_mov_b32_e32 v104, s25
	v_ashrrev_i32_e32 v147, 31, v146
	v_cndmask_b32_e32 v2, v2, v104, vcc
	s_mov_b32 s0, 0x1a000
	v_lshlrev_b64 v[110:111], 2, v[146:147]
	v_mad_i64_i32 v[104:105], s[0:1], v2, s0, v[140:141]
	v_lshl_add_u64 v[114:115], v[102:103], 0, v[110:111]
	v_lshl_add_u64 v[112:113], v[104:105], 0, v[110:111]
	global_load_dwordx4 v[180:183], v[114:115], off
	global_load_dwordx4 v[184:187], v[112:113], off
	global_load_dwordx4 v[188:191], v[112:113], off offset:64
	global_load_dwordx4 v[192:195], v[114:115], off offset:64
	global_load_dwordx4 v[196:199], v[112:113], off offset:512
	global_load_dwordx4 v[202:205], v[114:115], off offset:512
	global_load_dwordx4 v[206:209], v[112:113], off offset:576
	global_load_dwordx4 v[210:213], v[114:115], off offset:576
	v_lshl_add_u64 v[100:101], s[12:13], 0, v[100:101]
	v_lshl_add_u64 v[110:111], v[100:101], 0, v[110:111]
	s_waitcnt vmcnt(0)
	v_pk_fma_f32 v[98:99], v[98:99], v[186:187], v[182:183]
	v_pk_fma_f32 v[96:97], v[96:97], v[184:185], v[180:181]
	global_store_dwordx4 v[110:111], v[96:99], off
	v_pk_fma_f32 v[94:95], v[94:95], v[190:191], v[194:195]
	v_pk_fma_f32 v[92:93], v[92:93], v[188:189], v[192:193]
	global_store_dwordx4 v[110:111], v[92:95], off offset:64
	v_pk_fma_f32 v[90:91], v[90:91], v[198:199], v[204:205]
	v_pk_fma_f32 v[88:89], v[88:89], v[196:197], v[202:203]
	global_store_dwordx4 v[110:111], v[88:91], off offset:512
	v_pk_fma_f32 v[86:87], v[86:87], v[208:209], v[212:213]
	v_pk_fma_f32 v[84:85], v[84:85], v[206:207], v[210:211]
	global_store_dwordx4 v[110:111], v[84:87], off offset:576
.LBB0_1883:
	s_or_b64 exec, exec, s[22:23]
	v_or_b32_e32 v88, 48, v148
	s_movk_i32 s0, 0x4020
	v_cmp_gt_i32_e32 vcc, s0, v88
	s_and_saveexec_b64 s[22:23], vcc
	s_cbranch_execz .LBB0_1889
	s_movk_i32 s0, 0x4000
	v_cmp_gt_i32_e32 vcc, s0, v88
	s_movk_i32 s0, 0x3fff
	v_cmp_lt_i32_e64 s[0:1], s0, v88
	s_and_saveexec_b64 s[26:27], s[0:1]
	s_xor_b64 s[0:1], exec, s[26:27]
	v_add_u32_e32 v2, 0xffffc030, v148
	v_lshlrev_b64 v[84:85], 12, v[2:3]
	v_mov_b32_e32 v89, v3
	v_lshl_add_u64 v[86:87], v[132:133], 0, v[84:85]
	v_lshlrev_b64 v[84:85], 12, v[88:89]
	s_andn2_saveexec_b64 s[0:1], s[0:1]
	v_ashrrev_i32_e32 v89, 31, v88
	v_lshlrev_b64 v[84:85], 12, v[88:89]
	v_lshl_add_u64 v[86:87], s[12:13], 0, v[84:85]
	s_or_b64 exec, exec, s[0:1]
	v_add_u32_e32 v2, 0xffffc032, v148
	v_mov_b32_e32 v88, s25
	v_ashrrev_i32_e32 v147, 31, v146
	v_cndmask_b32_e32 v2, v2, v88, vcc
	s_mov_b32 s0, 0x1a000
	v_lshlrev_b64 v[94:95], 2, v[146:147]
	v_mad_i64_i32 v[88:89], s[0:1], v2, s0, v[140:141]
	v_lshl_add_u64 v[98:99], v[86:87], 0, v[94:95]
	v_lshl_add_u64 v[96:97], v[88:89], 0, v[94:95]
	global_load_dwordx4 v[180:183], v[98:99], off
	global_load_dwordx4 v[184:187], v[96:97], off
	global_load_dwordx4 v[188:191], v[96:97], off offset:64
	global_load_dwordx4 v[192:195], v[98:99], off offset:64
	global_load_dwordx4 v[196:199], v[96:97], off offset:512
	global_load_dwordx4 v[202:205], v[98:99], off offset:512
	global_load_dwordx4 v[206:209], v[96:97], off offset:576
	global_load_dwordx4 v[210:213], v[98:99], off offset:576
	v_lshl_add_u64 v[84:85], s[12:13], 0, v[84:85]
	v_lshl_add_u64 v[94:95], v[84:85], 0, v[94:95]
	s_waitcnt vmcnt(0)
	v_pk_fma_f32 v[82:83], v[82:83], v[186:187], v[182:183]
	v_pk_fma_f32 v[80:81], v[80:81], v[184:185], v[180:181]
	global_store_dwordx4 v[94:95], v[80:83], off
	v_pk_fma_f32 v[78:79], v[78:79], v[190:191], v[194:195]
	v_pk_fma_f32 v[76:77], v[76:77], v[188:189], v[192:193]
	global_store_dwordx4 v[94:95], v[76:79], off offset:64
	v_pk_fma_f32 v[74:75], v[74:75], v[198:199], v[204:205]
	v_pk_fma_f32 v[72:73], v[72:73], v[196:197], v[202:203]
	global_store_dwordx4 v[94:95], v[72:75], off offset:512
	v_pk_fma_f32 v[70:71], v[70:71], v[208:209], v[212:213]
	v_pk_fma_f32 v[68:69], v[68:69], v[206:207], v[210:211]
	global_store_dwordx4 v[94:95], v[68:71], off offset:576
.LBB0_1889:
	s_or_b64 exec, exec, s[22:23]
	s_addk_i32 s24, 0x80
	v_or_b32_e32 v68, s24, v154
	s_movk_i32 s0, 0x4020
	s_ashr_i32 s24, s24, 13
	v_cmp_gt_i32_e32 vcc, s0, v68
	s_and_saveexec_b64 s[22:23], vcc
	s_cbranch_execz .LBB0_1895
	s_movk_i32 s0, 0x4000
	v_cmp_gt_i32_e32 vcc, s0, v68
	s_movk_i32 s0, 0x3fff
	v_cmp_lt_i32_e64 s[0:1], s0, v68
	s_and_saveexec_b64 s[26:27], s[0:1]
	s_xor_b64 s[0:1], exec, s[26:27]
	v_add_u32_e32 v2, 0xffffc000, v68
	v_lshlrev_b64 v[70:71], 12, v[2:3]
	v_mov_b32_e32 v69, v3
	v_lshl_add_u64 v[72:73], v[132:133], 0, v[70:71]
	v_lshlrev_b64 v[70:71], 12, v[68:69]
	s_andn2_saveexec_b64 s[0:1], s[0:1]
	v_ashrrev_i32_e32 v69, 31, v68
	v_lshlrev_b64 v[70:71], 12, v[68:69]
	v_lshl_add_u64 v[72:73], s[12:13], 0, v[70:71]
	s_or_b64 exec, exec, s[0:1]
	v_add_u32_e32 v2, 0xffffc002, v68
	v_mov_b32_e32 v69, s24
	v_ashrrev_i32_e32 v147, 31, v146
	v_cndmask_b32_e32 v2, v2, v69, vcc
	s_mov_b32 s0, 0x1a000
	v_lshlrev_b64 v[80:81], 2, v[146:147]
	v_mad_i64_i32 v[74:75], s[0:1], v2, s0, v[140:141]
	v_lshl_add_u64 v[84:85], v[72:73], 0, v[80:81]
	v_lshl_add_u64 v[82:83], v[74:75], 0, v[80:81]
	global_load_dwordx4 v[180:183], v[84:85], off
	global_load_dwordx4 v[184:187], v[82:83], off
	global_load_dwordx4 v[188:191], v[82:83], off offset:64
	global_load_dwordx4 v[192:195], v[84:85], off offset:64
	global_load_dwordx4 v[196:199], v[82:83], off offset:512
	global_load_dwordx4 v[202:205], v[84:85], off offset:512
	global_load_dwordx4 v[206:209], v[82:83], off offset:576
	global_load_dwordx4 v[210:213], v[84:85], off offset:576
	v_lshl_add_u64 v[70:71], s[12:13], 0, v[70:71]
	v_lshl_add_u64 v[80:81], v[70:71], 0, v[80:81]
	s_waitcnt vmcnt(0)
	v_pk_fma_f32 v[66:67], v[66:67], v[186:187], v[182:183]
	v_pk_fma_f32 v[64:65], v[64:65], v[184:185], v[180:181]
	global_store_dwordx4 v[80:81], v[64:67], off
	v_pk_fma_f32 v[62:63], v[62:63], v[190:191], v[194:195]
	v_pk_fma_f32 v[60:61], v[60:61], v[188:189], v[192:193]
	global_store_dwordx4 v[80:81], v[60:63], off offset:64
	v_pk_fma_f32 v[58:59], v[58:59], v[198:199], v[204:205]
	v_pk_fma_f32 v[56:57], v[56:57], v[196:197], v[202:203]
	global_store_dwordx4 v[80:81], v[56:59], off offset:512
	v_pk_fma_f32 v[54:55], v[54:55], v[208:209], v[212:213]
	v_pk_fma_f32 v[52:53], v[52:53], v[206:207], v[210:211]
	global_store_dwordx4 v[80:81], v[52:55], off offset:576
.LBB0_1895:
	s_or_b64 exec, exec, s[22:23]
	v_or_b32_e32 v56, 16, v68
	s_movk_i32 s0, 0x4020
	v_cmp_gt_i32_e32 vcc, s0, v56
	s_and_saveexec_b64 s[22:23], vcc
	s_cbranch_execz .LBB0_1901
	s_movk_i32 s0, 0x4000
	v_cmp_gt_i32_e32 vcc, s0, v56
	s_movk_i32 s0, 0x3fff
	v_cmp_lt_i32_e64 s[0:1], s0, v56
	s_and_saveexec_b64 s[26:27], s[0:1]
	s_xor_b64 s[0:1], exec, s[26:27]
	v_add_u32_e32 v2, 0xffffc010, v68
	v_lshlrev_b64 v[52:53], 12, v[2:3]
	v_mov_b32_e32 v57, v3
	v_lshl_add_u64 v[54:55], v[132:133], 0, v[52:53]
	v_lshlrev_b64 v[52:53], 12, v[56:57]
	s_andn2_saveexec_b64 s[0:1], s[0:1]
	v_ashrrev_i32_e32 v57, 31, v56
	v_lshlrev_b64 v[52:53], 12, v[56:57]
	v_lshl_add_u64 v[54:55], s[12:13], 0, v[52:53]
	s_or_b64 exec, exec, s[0:1]
	v_add_u32_e32 v2, 0xffffc012, v68
	v_mov_b32_e32 v56, s24
	v_ashrrev_i32_e32 v147, 31, v146
	v_cndmask_b32_e32 v2, v2, v56, vcc
	s_mov_b32 s0, 0x1a000
	v_lshlrev_b64 v[62:63], 2, v[146:147]
	v_mad_i64_i32 v[56:57], s[0:1], v2, s0, v[140:141]
	v_lshl_add_u64 v[66:67], v[54:55], 0, v[62:63]
	v_lshl_add_u64 v[64:65], v[56:57], 0, v[62:63]
	global_load_dwordx4 v[180:183], v[66:67], off
	global_load_dwordx4 v[184:187], v[64:65], off
	global_load_dwordx4 v[188:191], v[64:65], off offset:64
	global_load_dwordx4 v[192:195], v[66:67], off offset:64
	global_load_dwordx4 v[196:199], v[64:65], off offset:512
	global_load_dwordx4 v[202:205], v[66:67], off offset:512
	global_load_dwordx4 v[206:209], v[64:65], off offset:576
	global_load_dwordx4 v[210:213], v[66:67], off offset:576
	v_lshl_add_u64 v[52:53], s[12:13], 0, v[52:53]
	v_lshl_add_u64 v[62:63], v[52:53], 0, v[62:63]
	s_waitcnt vmcnt(0)
	v_pk_fma_f32 v[50:51], v[50:51], v[186:187], v[182:183]
	v_pk_fma_f32 v[48:49], v[48:49], v[184:185], v[180:181]
	global_store_dwordx4 v[62:63], v[48:51], off
	v_pk_fma_f32 v[46:47], v[46:47], v[190:191], v[194:195]
	v_pk_fma_f32 v[44:45], v[44:45], v[188:189], v[192:193]
	global_store_dwordx4 v[62:63], v[44:47], off offset:64
	v_pk_fma_f32 v[42:43], v[42:43], v[198:199], v[204:205]
	v_pk_fma_f32 v[40:41], v[40:41], v[196:197], v[202:203]
	global_store_dwordx4 v[62:63], v[40:43], off offset:512
	v_pk_fma_f32 v[38:39], v[38:39], v[208:209], v[212:213]
	v_pk_fma_f32 v[36:37], v[36:37], v[206:207], v[210:211]
	global_store_dwordx4 v[62:63], v[36:39], off offset:576
.LBB0_1901:
	s_or_b64 exec, exec, s[22:23]
	v_or_b32_e32 v40, 32, v68
	s_movk_i32 s0, 0x4020
	v_cmp_gt_i32_e32 vcc, s0, v40
	s_and_saveexec_b64 s[22:23], vcc
	s_cbranch_execz .LBB0_1907
	s_movk_i32 s0, 0x4000
	v_cmp_gt_i32_e32 vcc, s0, v40
	s_movk_i32 s0, 0x3fff
	v_cmp_lt_i32_e64 s[0:1], s0, v40
	s_and_saveexec_b64 s[26:27], s[0:1]
	s_xor_b64 s[0:1], exec, s[26:27]
	v_add_u32_e32 v2, 0xffffc020, v68
	v_lshlrev_b64 v[36:37], 12, v[2:3]
	v_mov_b32_e32 v41, v3
	v_lshl_add_u64 v[38:39], v[132:133], 0, v[36:37]
	v_lshlrev_b64 v[36:37], 12, v[40:41]
	s_andn2_saveexec_b64 s[0:1], s[0:1]
	v_ashrrev_i32_e32 v41, 31, v40
	v_lshlrev_b64 v[36:37], 12, v[40:41]
	v_lshl_add_u64 v[38:39], s[12:13], 0, v[36:37]
	s_or_b64 exec, exec, s[0:1]
	v_add_u32_e32 v2, 0xffffc022, v68
	v_mov_b32_e32 v40, s24
	v_ashrrev_i32_e32 v147, 31, v146
	v_cndmask_b32_e32 v2, v2, v40, vcc
	s_mov_b32 s0, 0x1a000
	v_lshlrev_b64 v[46:47], 2, v[146:147]
	v_mad_i64_i32 v[40:41], s[0:1], v2, s0, v[140:141]
	v_lshl_add_u64 v[50:51], v[38:39], 0, v[46:47]
	v_lshl_add_u64 v[48:49], v[40:41], 0, v[46:47]
	global_load_dwordx4 v[180:183], v[50:51], off
	global_load_dwordx4 v[184:187], v[48:49], off
	global_load_dwordx4 v[188:191], v[48:49], off offset:64
	global_load_dwordx4 v[192:195], v[50:51], off offset:64
	global_load_dwordx4 v[196:199], v[48:49], off offset:512
	global_load_dwordx4 v[202:205], v[50:51], off offset:512
	global_load_dwordx4 v[206:209], v[48:49], off offset:576
	global_load_dwordx4 v[210:213], v[50:51], off offset:576
	v_lshl_add_u64 v[36:37], s[12:13], 0, v[36:37]
	v_lshl_add_u64 v[46:47], v[36:37], 0, v[46:47]
	s_waitcnt vmcnt(0)
	v_pk_fma_f32 v[34:35], v[34:35], v[186:187], v[182:183]
	v_pk_fma_f32 v[32:33], v[32:33], v[184:185], v[180:181]
	global_store_dwordx4 v[46:47], v[32:35], off
	v_pk_fma_f32 v[30:31], v[30:31], v[190:191], v[194:195]
	v_pk_fma_f32 v[28:29], v[28:29], v[188:189], v[192:193]
	global_store_dwordx4 v[46:47], v[28:31], off offset:64
	v_pk_fma_f32 v[26:27], v[26:27], v[198:199], v[204:205]
	v_pk_fma_f32 v[24:25], v[24:25], v[196:197], v[202:203]
	global_store_dwordx4 v[46:47], v[24:27], off offset:512
	v_pk_fma_f32 v[22:23], v[22:23], v[208:209], v[212:213]
	v_pk_fma_f32 v[20:21], v[20:21], v[206:207], v[210:211]
	global_store_dwordx4 v[46:47], v[20:23], off offset:576
.LBB0_1907:
	s_or_b64 exec, exec, s[22:23]
	v_or_b32_e32 v24, 48, v68
	s_movk_i32 s0, 0x4020
	v_cmp_gt_i32_e32 vcc, s0, v24
	s_and_saveexec_b64 s[22:23], vcc
	s_cbranch_execz .LBB0_1913
	s_movk_i32 s0, 0x4000
	v_cmp_gt_i32_e32 vcc, s0, v24
	s_movk_i32 s0, 0x3fff
	v_cmp_lt_i32_e64 s[0:1], s0, v24
	s_and_saveexec_b64 s[26:27], s[0:1]
	s_xor_b64 s[0:1], exec, s[26:27]
	v_add_u32_e32 v2, 0xffffc030, v68
	v_lshlrev_b64 v[20:21], 12, v[2:3]
	v_mov_b32_e32 v25, v3
	v_lshl_add_u64 v[22:23], v[132:133], 0, v[20:21]
	v_lshlrev_b64 v[20:21], 12, v[24:25]
	s_andn2_saveexec_b64 s[0:1], s[0:1]
	v_ashrrev_i32_e32 v25, 31, v24
	v_lshlrev_b64 v[20:21], 12, v[24:25]
	v_lshl_add_u64 v[22:23], s[12:13], 0, v[20:21]
	s_or_b64 exec, exec, s[0:1]
	v_add_u32_e32 v2, 0xffffc032, v68
	v_mov_b32_e32 v24, s24
	v_ashrrev_i32_e32 v147, 31, v146
	v_cndmask_b32_e32 v2, v2, v24, vcc
	s_mov_b32 s0, 0x1a000
	v_lshlrev_b64 v[30:31], 2, v[146:147]
	v_mad_i64_i32 v[24:25], s[0:1], v2, s0, v[140:141]
	v_lshl_add_u64 v[34:35], v[22:23], 0, v[30:31]
	v_lshl_add_u64 v[32:33], v[24:25], 0, v[30:31]
	global_load_dwordx4 v[180:183], v[34:35], off
	global_load_dwordx4 v[184:187], v[32:33], off
	global_load_dwordx4 v[188:191], v[32:33], off offset:64
	global_load_dwordx4 v[192:195], v[34:35], off offset:64
	global_load_dwordx4 v[196:199], v[32:33], off offset:512
	global_load_dwordx4 v[202:205], v[34:35], off offset:512
	global_load_dwordx4 v[206:209], v[32:33], off offset:576
	global_load_dwordx4 v[210:213], v[34:35], off offset:576
	v_lshl_add_u64 v[20:21], s[12:13], 0, v[20:21]
	v_lshl_add_u64 v[30:31], v[20:21], 0, v[30:31]
	s_waitcnt vmcnt(0)
	v_pk_fma_f32 v[18:19], v[18:19], v[186:187], v[182:183]
	v_pk_fma_f32 v[16:17], v[16:17], v[184:185], v[180:181]
	global_store_dwordx4 v[30:31], v[16:19], off
	v_pk_fma_f32 v[14:15], v[14:15], v[190:191], v[194:195]
	v_pk_fma_f32 v[12:13], v[12:13], v[188:189], v[192:193]
	global_store_dwordx4 v[30:31], v[12:15], off offset:64
	v_pk_fma_f32 v[10:11], v[10:11], v[198:199], v[204:205]
	v_pk_fma_f32 v[8:9], v[8:9], v[196:197], v[202:203]
	global_store_dwordx4 v[30:31], v[8:11], off offset:512
	v_pk_fma_f32 v[6:7], v[6:7], v[208:209], v[212:213]
	v_pk_fma_f32 v[4:5], v[4:5], v[206:207], v[210:211]
	global_store_dwordx4 v[30:31], v[4:7], off offset:576
